# 64-byte alignment of the six 8-phase GEMM K-loop heads (code placement lever)
# baseline (speedup 1.0000x reference)
.LBB0_215:
	s_or_b64 exec, exec, s[46:47]
	v_readlane_b32 s5, v250, 18
	s_mov_b64 s[8:9], 0x80
	v_lshl_add_u64 v[0:1], v[0:1], 0, s[8:9]
	v_add_u32_e32 v157, s5, v17
	v_add_u32_e32 v158, 0x2000, v157
	v_readfirstlane_b32 s43, v157
	s_mov_b32 m0, s43
	v_readfirstlane_b32 s43, v158
	v_add_u32_e32 v159, 0x8000, v150
	s_waitcnt vmcnt(4)
	s_barrier
	global_load_lds_dwordx4 v[0:1], off
	v_lshl_add_u64 v[0:1], v[2:3], 0, s[8:9]
	s_mov_b32 m0, s43
	v_readfirstlane_b32 s43, v159
	v_add_u32_e32 v160, 0xa000, v150
	v_readlane_b32 s6, v250, 19
	global_load_lds_dwordx4 v[0:1], off
	v_lshl_add_u64 v[0:1], v[4:5], 0, s[8:9]
	s_mov_b32 m0, s43
	v_readfirstlane_b32 s43, v160
	v_add_u32_e32 v161, s6, v17
	global_load_lds_dwordx4 v[0:1], off
	v_lshl_add_u64 v[0:1], v[6:7], 0, s[8:9]
	s_mov_b32 m0, s43
	v_readfirstlane_b32 s43, v161
	v_add_u32_e32 v162, 0x2000, v161
	global_load_lds_dwordx4 v[0:1], off
	v_lshl_add_u64 v[0:1], v[10:11], 0, s[8:9]
	s_mov_b32 m0, s43
	v_readfirstlane_b32 s43, v162
	global_load_lds_dwordx4 v[0:1], off
	v_lshl_add_u64 v[0:1], v[8:9], 0, s[8:9]
	s_mov_b32 m0, s43
	v_and_b32_e32 v143, 15, v140
	global_load_lds_dwordx4 v[0:1], off
	v_bfe_u32 v142, v140, 4, 2
	v_lshlrev_b32_e32 v3, 2, v140
	v_lshlrev_b32_e32 v0, 4, v142
	v_lshlrev_b32_e32 v1, 6, v143
	v_and_b32_e32 v3, 32, v3
	v_bitop3_b32 v1, v0, v3, v1 bitop3:0x36
	v_readlane_b32 s4, v250, 17
	v_add_u32_e32 v4, s41, v1
	v_add_u32_e32 v6, s5, v1
	v_add_u32_e32 v5, s4, v1
	v_add_u32_e32 v7, s6, v1
	v_add_u32_e32 v9, 0, v1
	v_lshlrev_b32_e32 v1, 6, v140
	s_movk_i32 s4, 0x3c0
	v_and_or_b32 v0, v1, s4, v0
	v_xad_u32 v3, v0, v3, 0
	v_add3_u32 v0, v22, v18, v20
	v_lshl_or_b32 v0, v0, 11, v15
	v_add_u32_sdwa v0, v0, sext(v14) dst_sel:DWORD dst_unused:UNUSED_PAD src0_sel:DWORD src1_sel:WORD_0
	v_mov_b32_e32 v1, v169
	v_lshl_add_u64 v[132:133], v[0:1], 1, s[44:45]
	v_add3_u32 v0, v23, v19, v21
	v_lshl_or_b32 v0, v0, 11, v24
	v_add_u32_sdwa v0, v0, sext(v16) dst_sel:DWORD dst_unused:UNUSED_PAD src0_sel:DWORD src1_sel:WORD_0
	v_lshl_add_u64 v[134:135], v[0:1], 1, s[44:45]
	s_sub_i32 s43, s51, s59
	s_lshl_b32 s44, s58, 8
	s_sub_i32 s43, s43, s44
	s_sext_i32_i16 s43, s43
	v_lshlrev_b32_e32 v0, 14, v12
	s_lshl_b32 s41, s58, 11
	s_lshl_b32 s43, s43, 8
	v_and_b32_e32 v0, 0xffff8000, v0
	s_add_i32 s44, s41, s43
	v_lshl_add_u32 v0, v13, 11, v0
	s_ashr_i32 s45, s44, 31
	v_or_b32_e32 v0, v0, v15
	v_bfe_u32 v141, v140, 6, 2
	s_waitcnt vmcnt(6)
	v_lshlrev_b32_e32 v8, 13, v25
	s_lshl_b64 s[44:45], s[44:45], 12
	v_add_u32_sdwa v0, v0, sext(v14) dst_sel:DWORD dst_unused:UNUSED_PAD src0_sel:DWORD src1_sel:WORD_0
	v_lshlrev_b32_e32 v2, 12, v141
	v_or_b32_e32 v10, 0x800, v8
	v_or_b32_e32 v11, 0x1000, v8
	v_or_b32_e32 v17, 0x1800, v8
	v_lshl_add_u64 v[136:137], v[0:1], 1, s[44:45]
	v_mov_b32_e32 v0, 0
	v_lshlrev_b32_e32 v144, 6, v25
	v_lshl_add_u64 v[138:139], v[168:169], 1, s[44:45]
	s_mov_b32 s41, -2
	v_add_u32_e32 v164, v4, v2
	v_add_u32_e32 v149, v9, v8
	v_add_u32_e32 v148, v3, v10
	v_add_u32_e32 v147, v3, v11
	v_add_u32_e32 v146, v3, v17
	v_add_u32_e32 v163, v5, v2
	v_add_u32_e32 v155, v6, v2
	v_add_u32_e32 v152, v7, v2
	s_mov_b64 s[44:45], s[38:39]
	v_mov_b32_e32 v1, v0
	v_mov_b32_e32 v2, v0
	v_mov_b32_e32 v3, v0
	v_mov_b32_e32 v4, v0
	v_mov_b32_e32 v5, v0
	v_mov_b32_e32 v6, v0
	v_mov_b32_e32 v7, v0
	v_mov_b32_e32 v8, v0
	v_mov_b32_e32 v9, v0
	v_mov_b32_e32 v10, v0
	v_mov_b32_e32 v11, v0
	v_mov_b32_e32 v12, v0
	v_mov_b32_e32 v13, v0
	v_mov_b32_e32 v14, v0
	v_mov_b32_e32 v15, v0
	v_mov_b32_e32 v16, v0
	v_mov_b32_e32 v17, v0
	v_mov_b32_e32 v18, v0
	v_mov_b32_e32 v19, v0
	v_mov_b32_e32 v20, v0
	v_mov_b32_e32 v21, v0
	v_mov_b32_e32 v22, v0
	v_mov_b32_e32 v23, v0
	v_mov_b32_e32 v24, v0
	v_mov_b32_e32 v25, v0
	v_mov_b32_e32 v26, v0
	v_mov_b32_e32 v27, v0
	v_mov_b32_e32 v28, v0
	v_mov_b32_e32 v29, v0
	v_mov_b32_e32 v30, v0
	v_mov_b32_e32 v31, v0
	v_mov_b32_e32 v32, v0
	v_mov_b32_e32 v33, v0
	v_mov_b32_e32 v34, v0
	v_mov_b32_e32 v35, v0
	v_mov_b32_e32 v36, v0
	v_mov_b32_e32 v37, v0
	v_mov_b32_e32 v38, v0
	v_mov_b32_e32 v39, v0
	v_mov_b32_e32 v40, v0
	v_mov_b32_e32 v41, v0
	v_mov_b32_e32 v42, v0
	v_mov_b32_e32 v43, v0
	v_mov_b32_e32 v44, v0
	v_mov_b32_e32 v45, v0
	v_mov_b32_e32 v46, v0
	v_mov_b32_e32 v47, v0
	v_mov_b32_e32 v48, v0
	v_mov_b32_e32 v49, v0
	v_mov_b32_e32 v50, v0
	v_mov_b32_e32 v51, v0
	v_mov_b32_e32 v52, v0
	v_mov_b32_e32 v53, v0
	v_mov_b32_e32 v54, v0
	v_mov_b32_e32 v55, v0
	v_mov_b32_e32 v56, v0
	v_mov_b32_e32 v57, v0
	v_mov_b32_e32 v58, v0
	v_mov_b32_e32 v59, v0
	v_mov_b32_e32 v60, v0
	v_mov_b32_e32 v61, v0
	v_mov_b32_e32 v62, v0
	v_mov_b32_e32 v63, v0
	v_mov_b32_e32 v64, v0
	v_mov_b32_e32 v65, v0
	v_mov_b32_e32 v66, v0
	v_mov_b32_e32 v67, v0
	v_mov_b32_e32 v68, v0
	v_mov_b32_e32 v69, v0
	v_mov_b32_e32 v70, v0
	v_mov_b32_e32 v71, v0
	v_mov_b32_e32 v72, v0
	v_mov_b32_e32 v73, v0
	v_mov_b32_e32 v74, v0
	v_mov_b32_e32 v75, v0
	v_mov_b32_e32 v76, v0
	v_mov_b32_e32 v77, v0
	v_mov_b32_e32 v78, v0
	v_mov_b32_e32 v79, v0
	v_mov_b32_e32 v80, v0
	v_mov_b32_e32 v81, v0
	v_mov_b32_e32 v82, v0
	v_mov_b32_e32 v83, v0
	v_mov_b32_e32 v84, v0
	v_mov_b32_e32 v85, v0
	v_mov_b32_e32 v86, v0
	v_mov_b32_e32 v87, v0
	v_mov_b32_e32 v88, v0
	v_mov_b32_e32 v89, v0
	v_mov_b32_e32 v90, v0
	v_mov_b32_e32 v91, v0
	v_mov_b32_e32 v92, v0
	v_mov_b32_e32 v93, v0
	v_mov_b32_e32 v94, v0
	v_mov_b32_e32 v95, v0
	v_mov_b32_e32 v96, v0
	v_mov_b32_e32 v97, v0
	v_mov_b32_e32 v98, v0
	v_mov_b32_e32 v99, v0
	v_mov_b32_e32 v100, v0
	v_mov_b32_e32 v101, v0
	v_mov_b32_e32 v102, v0
	v_mov_b32_e32 v103, v0
	v_mov_b32_e32 v104, v0
	v_mov_b32_e32 v105, v0
	v_mov_b32_e32 v106, v0
	v_mov_b32_e32 v107, v0
	v_mov_b32_e32 v108, v0
	v_mov_b32_e32 v109, v0
	v_mov_b32_e32 v110, v0
	v_mov_b32_e32 v111, v0
	v_mov_b32_e32 v112, v0
	v_mov_b32_e32 v113, v0
	v_mov_b32_e32 v114, v0
	v_mov_b32_e32 v115, v0
	v_mov_b32_e32 v116, v0
	v_mov_b32_e32 v117, v0
	v_mov_b32_e32 v118, v0
	v_mov_b32_e32 v119, v0
	v_mov_b32_e32 v120, v0
	v_mov_b32_e32 v121, v0
	v_mov_b32_e32 v122, v0
	v_mov_b32_e32 v123, v0
	v_mov_b32_e32 v124, v0
	v_mov_b32_e32 v125, v0
	v_mov_b32_e32 v126, v0
	v_mov_b32_e32 v127, v0
	s_mov_b64 s[4:5], 0x21528100
	s_mov_b64 s[6:7], 0x215a8100
	s_mov_b64 s[8:9], 0x21528180
	s_mov_b64 s[10:11], 0x215a8180
	s_barrier
	.p2align 6

.LBB0_868:
	s_or_b64 exec, exec, s[50:51]
	s_lshl_b32 s50, s84, 13
	s_and_b32 s50, s50, 0x180000
	s_add_i32 s50, s86, s50
	v_readlane_b32 s4, v250, 25
	s_and_b32 s6, s50, 0x380000
	s_lshl_b32 s50, s80, 19
	s_and_b32 s51, s81, 7
	v_readlane_b32 s5, v250, 26
	s_and_b32 s50, s50, 0xc00000
	s_lshl_b32 s51, s51, 19
	s_mov_b32 s7, s5
	s_or_b32 s50, s50, s51
	s_mov_b32 s51, s5
	v_readlane_b32 s5, v250, 18
	s_mov_b64 s[8:9], 0x80
	v_lshl_add_u64 v[2:3], v[2:3], 0, s[8:9]
	v_add_u32_e32 v157, s5, v13
	v_add_u32_e32 v158, 0x2000, v157
	v_readfirstlane_b32 s77, v157
	s_mov_b32 m0, s77
	v_readfirstlane_b32 s77, v158
	v_add_u32_e32 v159, 0x8000, v150
	s_waitcnt vmcnt(4)
	s_barrier
	global_load_lds_dwordx4 v[2:3], off
	v_lshl_add_u64 v[2:3], v[4:5], 0, s[8:9]
	s_mov_b32 m0, s77
	v_readfirstlane_b32 s77, v159
	global_load_lds_dwordx4 v[2:3], off
	v_lshl_add_u64 v[2:3], v[6:7], 0, s[8:9]
	s_mov_b32 m0, s77
	v_add_u32_e32 v160, 0xa000, v150
	global_load_lds_dwordx4 v[2:3], off
	v_lshl_add_u64 v[2:3], v[8:9], 0, s[8:9]
	v_readlane_b32 s8, v250, 19
	v_readfirstlane_b32 s77, v160
	s_add_u32 s48, s48, 0x40080
	v_add_u32_e32 v161, s8, v13
	s_mov_b32 m0, s77
	s_addc_u32 s49, s49, 0
	v_readfirstlane_b32 s77, v161
	v_add_u32_e32 v162, 0x2000, v161
	global_load_lds_dwordx4 v[2:3], off
	v_lshl_add_u64 v[2:3], v[168:169], 1, s[48:49]
	s_mov_b32 m0, s77
	v_lshl_add_u64 v[0:1], v[0:1], 1, s[48:49]
	v_readfirstlane_b32 s48, v162
	global_load_lds_dwordx4 v[2:3], off
	s_mov_b32 m0, s48
	v_and_b32_e32 v143, 15, v140
	global_load_lds_dwordx4 v[0:1], off
	v_bfe_u32 v142, v140, 4, 2
	v_lshlrev_b32_e32 v3, 2, v140
	v_lshlrev_b32_e32 v0, 4, v142
	v_lshlrev_b32_e32 v2, 6, v143
	v_and_b32_e32 v3, 32, v3
	v_bitop3_b32 v2, v0, v3, v2 bitop3:0x36
	v_readlane_b32 s4, v250, 17
	v_lshlrev_b32_e32 v9, 6, v140
	v_bfe_u32 v141, v140, 6, 2
	v_add_u32_e32 v5, s4, v2
	s_movk_i32 s4, 0x3c0
	v_and_or_b32 v0, v9, s4, v0
	v_xad_u32 v3, v0, v3, 0
	v_add3_u32 v0, v20, v16, v18
	v_lshl_or_b32 v0, v0, 10, v15
	v_add_u32_sdwa v168, v0, sext(v12) dst_sel:DWORD dst_unused:UNUSED_PAD src0_sel:DWORD src1_sel:WORD_0
	v_add3_u32 v0, v21, v17, v19
	v_lshl_or_b32 v0, v0, 10, v22
	v_lshl_add_u64 v[132:133], v[168:169], 1, s[6:7]
	v_add_u32_sdwa v168, v0, sext(v14) dst_sel:DWORD dst_unused:UNUSED_PAD src0_sel:DWORD src1_sel:WORD_0
	v_lshlrev_b32_e32 v0, 13, v10
	v_and_b32_e32 v0, 0xffffc000, v0
	v_lshl_add_u32 v0, v11, 10, v0
	s_waitcnt vmcnt(6)
	v_add_u32_e32 v6, s5, v2
	v_lshlrev_b32_e32 v8, 13, v23
	s_mov_b32 s5, s7
	v_or_b32_e32 v0, v0, v15
	v_lshlrev_b32_e32 v1, 12, v141
	v_add_u32_e32 v4, s85, v2
	v_lshlrev_b32_e32 v144, 6, v23
	v_add_u32_e32 v7, s8, v2
	v_add_u32_e32 v2, 0, v2
	v_or_b32_e32 v9, 0x800, v8
	v_or_b32_e32 v13, 0x1000, v8
	v_or_b32_e32 v23, 0x1800, v8
	v_writelane_b32 v250, s4, 25
	v_lshl_add_u64 v[134:135], v[168:169], 1, s[6:7]
	v_add_u32_sdwa v168, v0, sext(v12) dst_sel:DWORD dst_unused:UNUSED_PAD src0_sel:DWORD src1_sel:WORD_0
	v_mov_b32_e32 v0, 0
	v_writelane_b32 v250, s5, 26
	v_lshl_add_u64 v[136:137], v[168:169], 1, s[50:51]
	v_lshl_add_u64 v[138:139], v[128:129], 1, s[50:51]
	s_mov_b32 s50, -2
	v_add_u32_e32 v164, v4, v1
	v_add_u32_e32 v149, v2, v8
	v_add_u32_e32 v148, v3, v9
	v_add_u32_e32 v147, v3, v13
	v_add_u32_e32 v145, v3, v23
	v_add_u32_e32 v163, v5, v1
	v_add_u32_e32 v156, v6, v1
	v_add_u32_e32 v152, v7, v1
	s_mov_b64 s[48:49], s[42:43]
	v_mov_b32_e32 v1, v0
	v_mov_b32_e32 v2, v0
	v_mov_b32_e32 v3, v0
	v_mov_b32_e32 v4, v0
	v_mov_b32_e32 v5, v0
	v_mov_b32_e32 v6, v0
	v_mov_b32_e32 v7, v0
	v_mov_b32_e32 v8, v0
	v_mov_b32_e32 v9, v0
	v_mov_b32_e32 v10, v0
	v_mov_b32_e32 v11, v0
	v_mov_b32_e32 v12, v0
	v_mov_b32_e32 v13, v0
	v_mov_b32_e32 v14, v0
	v_mov_b32_e32 v15, v0
	v_mov_b32_e32 v16, v0
	v_mov_b32_e32 v17, v0
	v_mov_b32_e32 v18, v0
	v_mov_b32_e32 v19, v0
	v_mov_b32_e32 v20, v0
	v_mov_b32_e32 v21, v0
	v_mov_b32_e32 v22, v0
	v_mov_b32_e32 v23, v0
	v_mov_b32_e32 v24, v0
	v_mov_b32_e32 v25, v0
	v_mov_b32_e32 v26, v0
	v_mov_b32_e32 v27, v0
	v_mov_b32_e32 v28, v0
	v_mov_b32_e32 v29, v0
	v_mov_b32_e32 v30, v0
	v_mov_b32_e32 v31, v0
	v_mov_b32_e32 v32, v0
	v_mov_b32_e32 v33, v0
	v_mov_b32_e32 v34, v0
	v_mov_b32_e32 v35, v0
	v_mov_b32_e32 v36, v0
	v_mov_b32_e32 v37, v0
	v_mov_b32_e32 v38, v0
	v_mov_b32_e32 v39, v0
	v_mov_b32_e32 v40, v0
	v_mov_b32_e32 v41, v0
	v_mov_b32_e32 v42, v0
	v_mov_b32_e32 v43, v0
	v_mov_b32_e32 v44, v0
	v_mov_b32_e32 v45, v0
	v_mov_b32_e32 v46, v0
	v_mov_b32_e32 v47, v0
	v_mov_b32_e32 v48, v0
	v_mov_b32_e32 v49, v0
	v_mov_b32_e32 v50, v0
	v_mov_b32_e32 v51, v0
	v_mov_b32_e32 v52, v0
	v_mov_b32_e32 v53, v0
	v_mov_b32_e32 v54, v0
	v_mov_b32_e32 v55, v0
	v_mov_b32_e32 v56, v0
	v_mov_b32_e32 v57, v0
	v_mov_b32_e32 v58, v0
	v_mov_b32_e32 v59, v0
	v_mov_b32_e32 v60, v0
	v_mov_b32_e32 v61, v0
	v_mov_b32_e32 v62, v0
	v_mov_b32_e32 v63, v0
	v_mov_b32_e32 v64, v0
	v_mov_b32_e32 v65, v0
	v_mov_b32_e32 v66, v0
	v_mov_b32_e32 v67, v0
	v_mov_b32_e32 v68, v0
	v_mov_b32_e32 v69, v0
	v_mov_b32_e32 v70, v0
	v_mov_b32_e32 v71, v0
	v_mov_b32_e32 v72, v0
	v_mov_b32_e32 v73, v0
	v_mov_b32_e32 v74, v0
	v_mov_b32_e32 v75, v0
	v_mov_b32_e32 v76, v0
	v_mov_b32_e32 v77, v0
	v_mov_b32_e32 v78, v0
	v_mov_b32_e32 v79, v0
	v_mov_b32_e32 v80, v0
	v_mov_b32_e32 v81, v0
	v_mov_b32_e32 v82, v0
	v_mov_b32_e32 v83, v0
	v_mov_b32_e32 v84, v0
	v_mov_b32_e32 v85, v0
	v_mov_b32_e32 v86, v0
	v_mov_b32_e32 v87, v0
	v_mov_b32_e32 v88, v0
	v_mov_b32_e32 v89, v0
	v_mov_b32_e32 v90, v0
	v_mov_b32_e32 v91, v0
	v_mov_b32_e32 v92, v0
	v_mov_b32_e32 v93, v0
	v_mov_b32_e32 v94, v0
	v_mov_b32_e32 v95, v0
	v_mov_b32_e32 v96, v0
	v_mov_b32_e32 v97, v0
	v_mov_b32_e32 v98, v0
	v_mov_b32_e32 v99, v0
	v_mov_b32_e32 v100, v0
	v_mov_b32_e32 v101, v0
	v_mov_b32_e32 v102, v0
	v_mov_b32_e32 v103, v0
	v_mov_b32_e32 v104, v0
	v_mov_b32_e32 v105, v0
	v_mov_b32_e32 v106, v0
	v_mov_b32_e32 v107, v0
	v_mov_b32_e32 v108, v0
	v_mov_b32_e32 v109, v0
	v_mov_b32_e32 v110, v0
	v_mov_b32_e32 v111, v0
	v_mov_b32_e32 v112, v0
	v_mov_b32_e32 v113, v0
	v_mov_b32_e32 v114, v0
	v_mov_b32_e32 v115, v0
	v_mov_b32_e32 v116, v0
	v_mov_b32_e32 v117, v0
	v_mov_b32_e32 v118, v0
	v_mov_b32_e32 v119, v0
	v_mov_b32_e32 v120, v0
	v_mov_b32_e32 v121, v0
	v_mov_b32_e32 v122, v0
	v_mov_b32_e32 v123, v0
	v_mov_b32_e32 v124, v0
	v_mov_b32_e32 v125, v0
	v_mov_b32_e32 v126, v0
	v_mov_b32_e32 v127, v0
	s_mov_b64 s[4:5], 0xfce8080
	s_mov_b64 s[6:7], 0x241a8100
	s_mov_b64 s[8:9], 0xfca8100
	s_mov_b64 s[10:11], 0x241e8100
	s_mov_b64 s[12:13], 0xfce8100
	s_mov_b64 s[14:15], 0x241a8180
	s_mov_b64 s[16:17], 0xfca8180
	s_mov_b64 s[18:19], 0x241e8180
	s_barrier
	.p2align 6

.LBB0_943:
	s_or_b64 exec, exec, s[58:59]
	v_readlane_b32 s4, v250, 18
	s_mov_b64 s[6:7], 0x80
	v_lshl_add_u64 v[0:1], v[0:1], 0, s[6:7]
	v_add_u32_e32 v157, s4, v17
	v_add_u32_e32 v158, 0x2000, v157
	v_readfirstlane_b32 s49, v157
	s_mov_b32 m0, s49
	v_readfirstlane_b32 s49, v158
	v_add_u32_e32 v159, 0x8000, v150
	s_waitcnt vmcnt(4)
	s_barrier
	global_load_lds_dwordx4 v[0:1], off
	v_lshl_add_u64 v[0:1], v[2:3], 0, s[6:7]
	s_mov_b32 m0, s49
	v_readfirstlane_b32 s49, v159
	v_add_u32_e32 v160, 0xa000, v150
	v_readlane_b32 s5, v250, 19
	global_load_lds_dwordx4 v[0:1], off
	v_lshl_add_u64 v[0:1], v[4:5], 0, s[6:7]
	s_mov_b32 m0, s49
	v_readfirstlane_b32 s49, v160
	v_add_u32_e32 v161, s5, v17
	global_load_lds_dwordx4 v[0:1], off
	v_lshl_add_u64 v[0:1], v[6:7], 0, s[6:7]
	s_mov_b32 m0, s49
	v_readfirstlane_b32 s49, v161
	v_add_u32_e32 v162, 0x2000, v161
	global_load_lds_dwordx4 v[0:1], off
	v_lshl_add_u64 v[0:1], v[10:11], 0, s[6:7]
	s_mov_b32 m0, s49
	v_readfirstlane_b32 s49, v162
	global_load_lds_dwordx4 v[0:1], off
	v_lshl_add_u64 v[0:1], v[8:9], 0, s[6:7]
	s_mov_b32 m0, s49
	v_and_b32_e32 v143, 15, v140
	global_load_lds_dwordx4 v[0:1], off
	v_bfe_u32 v142, v140, 4, 2
	v_lshlrev_b32_e32 v3, 2, v140
	v_lshlrev_b32_e32 v0, 4, v142
	v_lshlrev_b32_e32 v1, 6, v143
	v_and_b32_e32 v3, 32, v3
	v_bitop3_b32 v1, v0, v3, v1 bitop3:0x36
	v_add_u32_e32 v4, s1, v1
	v_readlane_b32 s1, v250, 17
	v_add_u32_e32 v6, s4, v1
	v_add_u32_e32 v7, s5, v1
	v_add_u32_e32 v5, s1, v1
	v_add_u32_e32 v9, 0, v1
	v_lshlrev_b32_e32 v1, 6, v140
	s_movk_i32 s1, 0x3c0
	v_and_or_b32 v0, v1, s1, v0
	v_xad_u32 v3, v0, v3, 0
	v_add3_u32 v0, v22, v18, v20
	v_lshl_or_b32 v0, v0, 11, v15
	v_add_u32_sdwa v0, v0, sext(v14) dst_sel:DWORD dst_unused:UNUSED_PAD src0_sel:DWORD src1_sel:WORD_0
	v_mov_b32_e32 v1, v169
	v_lshl_add_u64 v[132:133], v[0:1], 1, s[50:51]
	v_add3_u32 v0, v23, v19, v21
	v_lshl_or_b32 v0, v0, 11, v24
	v_add_u32_sdwa v0, v0, sext(v16) dst_sel:DWORD dst_unused:UNUSED_PAD src0_sel:DWORD src1_sel:WORD_0
	v_lshl_add_u64 v[134:135], v[0:1], 1, s[50:51]
	s_sub_i32 s49, s85, s87
	s_lshl_b32 s50, s86, 6
	s_sub_i32 s49, s49, s50
	s_sext_i32_i8 s49, s49
	v_lshlrev_b32_e32 v0, 14, v12
	s_lshl_b32 s1, s86, 11
	s_lshl_b32 s49, s49, 8
	v_and_b32_e32 v0, 0xffff8000, v0
	s_add_i32 s50, s1, s49
	v_lshl_add_u32 v0, v13, 11, v0
	s_ashr_i32 s51, s50, 31
	v_or_b32_e32 v0, v0, v15
	v_bfe_u32 v141, v140, 6, 2
	s_waitcnt vmcnt(6)
	v_lshlrev_b32_e32 v8, 13, v25
	s_lshl_b64 s[50:51], s[50:51], 12
	v_add_u32_sdwa v0, v0, sext(v14) dst_sel:DWORD dst_unused:UNUSED_PAD src0_sel:DWORD src1_sel:WORD_0
	v_lshlrev_b32_e32 v2, 12, v141
	v_or_b32_e32 v10, 0x800, v8
	v_or_b32_e32 v11, 0x1000, v8
	v_or_b32_e32 v17, 0x1800, v8
	v_lshl_add_u64 v[136:137], v[0:1], 1, s[50:51]
	v_mov_b32_e32 v0, 0
	v_lshlrev_b32_e32 v144, 6, v25
	v_lshl_add_u64 v[138:139], v[168:169], 1, s[50:51]
	s_mov_b32 s1, -2
	v_add_u32_e32 v164, v4, v2
	v_add_u32_e32 v149, v9, v8
	v_add_u32_e32 v148, v3, v10
	v_add_u32_e32 v147, v3, v11
	v_add_u32_e32 v146, v3, v17
	v_add_u32_e32 v163, v5, v2
	v_add_u32_e32 v155, v6, v2
	v_add_u32_e32 v152, v7, v2
	s_mov_b64 s[50:51], s[46:47]
	v_mov_b32_e32 v1, v0
	v_mov_b32_e32 v2, v0
	v_mov_b32_e32 v3, v0
	v_mov_b32_e32 v4, v0
	v_mov_b32_e32 v5, v0
	v_mov_b32_e32 v6, v0
	v_mov_b32_e32 v7, v0
	v_mov_b32_e32 v8, v0
	v_mov_b32_e32 v9, v0
	v_mov_b32_e32 v10, v0
	v_mov_b32_e32 v11, v0
	v_mov_b32_e32 v12, v0
	v_mov_b32_e32 v13, v0
	v_mov_b32_e32 v14, v0
	v_mov_b32_e32 v15, v0
	v_mov_b32_e32 v16, v0
	v_mov_b32_e32 v17, v0
	v_mov_b32_e32 v18, v0
	v_mov_b32_e32 v19, v0
	v_mov_b32_e32 v20, v0
	v_mov_b32_e32 v21, v0
	v_mov_b32_e32 v22, v0
	v_mov_b32_e32 v23, v0
	v_mov_b32_e32 v24, v0
	v_mov_b32_e32 v25, v0
	v_mov_b32_e32 v26, v0
	v_mov_b32_e32 v27, v0
	v_mov_b32_e32 v28, v0
	v_mov_b32_e32 v29, v0
	v_mov_b32_e32 v30, v0
	v_mov_b32_e32 v31, v0
	v_mov_b32_e32 v32, v0
	v_mov_b32_e32 v33, v0
	v_mov_b32_e32 v34, v0
	v_mov_b32_e32 v35, v0
	v_mov_b32_e32 v36, v0
	v_mov_b32_e32 v37, v0
	v_mov_b32_e32 v38, v0
	v_mov_b32_e32 v39, v0
	v_mov_b32_e32 v40, v0
	v_mov_b32_e32 v41, v0
	v_mov_b32_e32 v42, v0
	v_mov_b32_e32 v43, v0
	v_mov_b32_e32 v44, v0
	v_mov_b32_e32 v45, v0
	v_mov_b32_e32 v46, v0
	v_mov_b32_e32 v47, v0
	v_mov_b32_e32 v48, v0
	v_mov_b32_e32 v49, v0
	v_mov_b32_e32 v50, v0
	v_mov_b32_e32 v51, v0
	v_mov_b32_e32 v52, v0
	v_mov_b32_e32 v53, v0
	v_mov_b32_e32 v54, v0
	v_mov_b32_e32 v55, v0
	v_mov_b32_e32 v56, v0
	v_mov_b32_e32 v57, v0
	v_mov_b32_e32 v58, v0
	v_mov_b32_e32 v59, v0
	v_mov_b32_e32 v60, v0
	v_mov_b32_e32 v61, v0
	v_mov_b32_e32 v62, v0
	v_mov_b32_e32 v63, v0
	v_mov_b32_e32 v64, v0
	v_mov_b32_e32 v65, v0
	v_mov_b32_e32 v66, v0
	v_mov_b32_e32 v67, v0
	v_mov_b32_e32 v68, v0
	v_mov_b32_e32 v69, v0
	v_mov_b32_e32 v70, v0
	v_mov_b32_e32 v71, v0
	v_mov_b32_e32 v72, v0
	v_mov_b32_e32 v73, v0
	v_mov_b32_e32 v74, v0
	v_mov_b32_e32 v75, v0
	v_mov_b32_e32 v76, v0
	v_mov_b32_e32 v77, v0
	v_mov_b32_e32 v78, v0
	v_mov_b32_e32 v79, v0
	v_mov_b32_e32 v80, v0
	v_mov_b32_e32 v81, v0
	v_mov_b32_e32 v82, v0
	v_mov_b32_e32 v83, v0
	v_mov_b32_e32 v84, v0
	v_mov_b32_e32 v85, v0
	v_mov_b32_e32 v86, v0
	v_mov_b32_e32 v87, v0
	v_mov_b32_e32 v88, v0
	v_mov_b32_e32 v89, v0
	v_mov_b32_e32 v90, v0
	v_mov_b32_e32 v91, v0
	v_mov_b32_e32 v92, v0
	v_mov_b32_e32 v93, v0
	v_mov_b32_e32 v94, v0
	v_mov_b32_e32 v95, v0
	v_mov_b32_e32 v96, v0
	v_mov_b32_e32 v97, v0
	v_mov_b32_e32 v98, v0
	v_mov_b32_e32 v99, v0
	v_mov_b32_e32 v100, v0
	v_mov_b32_e32 v101, v0
	v_mov_b32_e32 v102, v0
	v_mov_b32_e32 v103, v0
	v_mov_b32_e32 v104, v0
	v_mov_b32_e32 v105, v0
	v_mov_b32_e32 v106, v0
	v_mov_b32_e32 v107, v0
	v_mov_b32_e32 v108, v0
	v_mov_b32_e32 v109, v0
	v_mov_b32_e32 v110, v0
	v_mov_b32_e32 v111, v0
	v_mov_b32_e32 v112, v0
	v_mov_b32_e32 v113, v0
	v_mov_b32_e32 v114, v0
	v_mov_b32_e32 v115, v0
	v_mov_b32_e32 v116, v0
	v_mov_b32_e32 v117, v0
	v_mov_b32_e32 v118, v0
	v_mov_b32_e32 v119, v0
	v_mov_b32_e32 v120, v0
	v_mov_b32_e32 v121, v0
	v_mov_b32_e32 v122, v0
	v_mov_b32_e32 v123, v0
	v_mov_b32_e32 v124, v0
	v_mov_b32_e32 v125, v0
	v_mov_b32_e32 v126, v0
	v_mov_b32_e32 v127, v0
	s_mov_b64 s[4:5], 0x191a8080
	s_mov_b64 s[6:7], 0x23928100
	s_mov_b64 s[8:9], 0x19128100
	s_mov_b64 s[10:11], 0x239a8100
	s_mov_b64 s[12:13], 0x191a8100
	s_barrier
	.p2align 6

.LBB0_1009:
	s_or_b64 exec, exec, s[46:47]
	v_readlane_b32 s4, v250, 18
	s_mov_b64 s[6:7], 0x80
	v_lshl_add_u64 v[0:1], v[0:1], 0, s[6:7]
	v_add_u32_e32 v157, s4, v17
	v_add_u32_e32 v158, 0x2000, v157
	v_readfirstlane_b32 s39, v157
	s_mov_b32 m0, s39
	v_readfirstlane_b32 s39, v158
	v_add_u32_e32 v159, 0x8000, v150
	s_waitcnt vmcnt(4)
	s_barrier
	global_load_lds_dwordx4 v[0:1], off
	v_lshl_add_u64 v[0:1], v[2:3], 0, s[6:7]
	s_mov_b32 m0, s39
	v_readfirstlane_b32 s39, v159
	v_add_u32_e32 v160, 0xa000, v150
	v_readlane_b32 s5, v250, 19
	global_load_lds_dwordx4 v[0:1], off
	v_lshl_add_u64 v[0:1], v[4:5], 0, s[6:7]
	s_mov_b32 m0, s39
	v_readfirstlane_b32 s39, v160
	v_add_u32_e32 v161, s5, v17
	global_load_lds_dwordx4 v[0:1], off
	v_lshl_add_u64 v[0:1], v[6:7], 0, s[6:7]
	s_mov_b32 m0, s39
	v_readfirstlane_b32 s39, v161
	v_add_u32_e32 v162, 0x2000, v161
	global_load_lds_dwordx4 v[0:1], off
	v_lshl_add_u64 v[0:1], v[10:11], 0, s[6:7]
	s_mov_b32 m0, s39
	v_readfirstlane_b32 s39, v162
	global_load_lds_dwordx4 v[0:1], off
	v_lshl_add_u64 v[0:1], v[8:9], 0, s[6:7]
	s_mov_b32 m0, s39
	v_and_b32_e32 v143, 15, v140
	global_load_lds_dwordx4 v[0:1], off
	v_bfe_u32 v142, v140, 4, 2
	v_lshlrev_b32_e32 v3, 2, v140
	v_lshlrev_b32_e32 v0, 4, v142
	v_lshlrev_b32_e32 v1, 6, v143
	v_and_b32_e32 v3, 32, v3
	v_bitop3_b32 v1, v0, v3, v1 bitop3:0x36
	v_add_u32_e32 v4, s1, v1
	v_readlane_b32 s1, v250, 17
	v_add_u32_e32 v6, s4, v1
	v_add_u32_e32 v7, s5, v1
	v_add_u32_e32 v5, s1, v1
	v_add_u32_e32 v9, 0, v1
	v_lshlrev_b32_e32 v1, 6, v140
	s_movk_i32 s1, 0x3c0
	v_and_or_b32 v0, v1, s1, v0
	v_xad_u32 v3, v0, v3, 0
	v_add3_u32 v0, v22, v18, v20
	v_lshl_or_b32 v0, v0, 11, v15
	v_add_u32_sdwa v0, v0, sext(v14) dst_sel:DWORD dst_unused:UNUSED_PAD src0_sel:DWORD src1_sel:WORD_0
	v_mov_b32_e32 v1, v169
	v_lshl_add_u64 v[132:133], v[0:1], 1, s[44:45]
	v_add3_u32 v0, v23, v19, v21
	v_lshl_or_b32 v0, v0, 11, v24
	v_add_u32_sdwa v0, v0, sext(v16) dst_sel:DWORD dst_unused:UNUSED_PAD src0_sel:DWORD src1_sel:WORD_0
	v_lshl_add_u64 v[134:135], v[0:1], 1, s[44:45]
	s_sub_i32 s39, s51, s59
	s_lshl_b32 s44, s58, 6
	s_sub_i32 s39, s39, s44
	s_sext_i32_i8 s39, s39
	v_lshlrev_b32_e32 v0, 14, v12
	s_lshl_b32 s1, s58, 11
	s_lshl_b32 s39, s39, 8
	v_and_b32_e32 v0, 0xffff8000, v0
	s_add_i32 s44, s1, s39
	v_lshl_add_u32 v0, v13, 11, v0
	s_ashr_i32 s45, s44, 31
	v_or_b32_e32 v0, v0, v15
	v_bfe_u32 v141, v140, 6, 2
	s_waitcnt vmcnt(6)
	v_lshlrev_b32_e32 v8, 13, v25
	s_lshl_b64 s[44:45], s[44:45], 12
	v_add_u32_sdwa v0, v0, sext(v14) dst_sel:DWORD dst_unused:UNUSED_PAD src0_sel:DWORD src1_sel:WORD_0
	v_lshlrev_b32_e32 v2, 12, v141
	v_or_b32_e32 v10, 0x800, v8
	v_or_b32_e32 v11, 0x1000, v8
	v_or_b32_e32 v17, 0x1800, v8
	v_lshl_add_u64 v[136:137], v[0:1], 1, s[44:45]
	v_mov_b32_e32 v0, 0
	v_lshlrev_b32_e32 v144, 6, v25
	v_lshl_add_u64 v[138:139], v[168:169], 1, s[44:45]
	s_mov_b32 s1, -2
	v_add_u32_e32 v164, v4, v2
	v_add_u32_e32 v149, v9, v8
	v_add_u32_e32 v148, v3, v10
	v_add_u32_e32 v147, v3, v11
	v_add_u32_e32 v146, v3, v17
	v_add_u32_e32 v163, v5, v2
	v_add_u32_e32 v156, v6, v2
	v_add_u32_e32 v152, v7, v2
	s_mov_b64 s[44:45], s[40:41]
	v_mov_b32_e32 v1, v0
	v_mov_b32_e32 v2, v0
	v_mov_b32_e32 v3, v0
	v_mov_b32_e32 v4, v0
	v_mov_b32_e32 v5, v0
	v_mov_b32_e32 v6, v0
	v_mov_b32_e32 v7, v0
	v_mov_b32_e32 v8, v0
	v_mov_b32_e32 v9, v0
	v_mov_b32_e32 v10, v0
	v_mov_b32_e32 v11, v0
	v_mov_b32_e32 v12, v0
	v_mov_b32_e32 v13, v0
	v_mov_b32_e32 v14, v0
	v_mov_b32_e32 v15, v0
	v_mov_b32_e32 v16, v0
	v_mov_b32_e32 v17, v0
	v_mov_b32_e32 v18, v0
	v_mov_b32_e32 v19, v0
	v_mov_b32_e32 v20, v0
	v_mov_b32_e32 v21, v0
	v_mov_b32_e32 v22, v0
	v_mov_b32_e32 v23, v0
	v_mov_b32_e32 v24, v0
	v_mov_b32_e32 v25, v0
	v_mov_b32_e32 v26, v0
	v_mov_b32_e32 v27, v0
	v_mov_b32_e32 v28, v0
	v_mov_b32_e32 v29, v0
	v_mov_b32_e32 v30, v0
	v_mov_b32_e32 v31, v0
	v_mov_b32_e32 v32, v0
	v_mov_b32_e32 v33, v0
	v_mov_b32_e32 v34, v0
	v_mov_b32_e32 v35, v0
	v_mov_b32_e32 v36, v0
	v_mov_b32_e32 v37, v0
	v_mov_b32_e32 v38, v0
	v_mov_b32_e32 v39, v0
	v_mov_b32_e32 v40, v0
	v_mov_b32_e32 v41, v0
	v_mov_b32_e32 v42, v0
	v_mov_b32_e32 v43, v0
	v_mov_b32_e32 v44, v0
	v_mov_b32_e32 v45, v0
	v_mov_b32_e32 v46, v0
	v_mov_b32_e32 v47, v0
	v_mov_b32_e32 v48, v0
	v_mov_b32_e32 v49, v0
	v_mov_b32_e32 v50, v0
	v_mov_b32_e32 v51, v0
	v_mov_b32_e32 v52, v0
	v_mov_b32_e32 v53, v0
	v_mov_b32_e32 v54, v0
	v_mov_b32_e32 v55, v0
	v_mov_b32_e32 v56, v0
	v_mov_b32_e32 v57, v0
	v_mov_b32_e32 v58, v0
	v_mov_b32_e32 v59, v0
	v_mov_b32_e32 v60, v0
	v_mov_b32_e32 v61, v0
	v_mov_b32_e32 v62, v0
	v_mov_b32_e32 v63, v0
	v_mov_b32_e32 v64, v0
	v_mov_b32_e32 v65, v0
	v_mov_b32_e32 v66, v0
	v_mov_b32_e32 v67, v0
	v_mov_b32_e32 v68, v0
	v_mov_b32_e32 v69, v0
	v_mov_b32_e32 v70, v0
	v_mov_b32_e32 v71, v0
	v_mov_b32_e32 v72, v0
	v_mov_b32_e32 v73, v0
	v_mov_b32_e32 v74, v0
	v_mov_b32_e32 v75, v0
	v_mov_b32_e32 v76, v0
	v_mov_b32_e32 v77, v0
	v_mov_b32_e32 v78, v0
	v_mov_b32_e32 v79, v0
	v_mov_b32_e32 v80, v0
	v_mov_b32_e32 v81, v0
	v_mov_b32_e32 v82, v0
	v_mov_b32_e32 v83, v0
	v_mov_b32_e32 v84, v0
	v_mov_b32_e32 v85, v0
	v_mov_b32_e32 v86, v0
	v_mov_b32_e32 v87, v0
	v_mov_b32_e32 v88, v0
	v_mov_b32_e32 v89, v0
	v_mov_b32_e32 v90, v0
	v_mov_b32_e32 v91, v0
	v_mov_b32_e32 v92, v0
	v_mov_b32_e32 v93, v0
	v_mov_b32_e32 v94, v0
	v_mov_b32_e32 v95, v0
	v_mov_b32_e32 v96, v0
	v_mov_b32_e32 v97, v0
	v_mov_b32_e32 v98, v0
	v_mov_b32_e32 v99, v0
	v_mov_b32_e32 v100, v0
	v_mov_b32_e32 v101, v0
	v_mov_b32_e32 v102, v0
	v_mov_b32_e32 v103, v0
	v_mov_b32_e32 v104, v0
	v_mov_b32_e32 v105, v0
	v_mov_b32_e32 v106, v0
	v_mov_b32_e32 v107, v0
	v_mov_b32_e32 v108, v0
	v_mov_b32_e32 v109, v0
	v_mov_b32_e32 v110, v0
	v_mov_b32_e32 v111, v0
	v_mov_b32_e32 v112, v0
	v_mov_b32_e32 v113, v0
	v_mov_b32_e32 v114, v0
	v_mov_b32_e32 v115, v0
	v_mov_b32_e32 v116, v0
	v_mov_b32_e32 v117, v0
	v_mov_b32_e32 v118, v0
	v_mov_b32_e32 v119, v0
	v_mov_b32_e32 v120, v0
	v_mov_b32_e32 v121, v0
	v_mov_b32_e32 v122, v0
	v_mov_b32_e32 v123, v0
	v_mov_b32_e32 v124, v0
	v_mov_b32_e32 v125, v0
	v_mov_b32_e32 v126, v0
	v_mov_b32_e32 v127, v0
	s_mov_b64 s[4:5], 0x1f4a8080
	s_barrier
	.p2align 6

.LBB0_1130:
	s_or_b64 exec, exec, s[48:49]
	v_readlane_b32 s5, v250, 18
	s_mov_b64 s[8:9], 0x80
	v_lshl_add_u64 v[0:1], v[0:1], 0, s[8:9]
	v_add_u32_e32 v157, s5, v17
	v_add_u32_e32 v158, 0x2000, v157
	v_readfirstlane_b32 s45, v157
	s_mov_b32 m0, s45
	v_readfirstlane_b32 s45, v158
	v_add_u32_e32 v159, 0x8000, v150
	s_waitcnt vmcnt(4)
	s_barrier
	global_load_lds_dwordx4 v[0:1], off
	v_lshl_add_u64 v[0:1], v[2:3], 0, s[8:9]
	s_mov_b32 m0, s45
	v_readfirstlane_b32 s45, v159
	v_add_u32_e32 v160, 0xa000, v150
	v_readlane_b32 s6, v250, 19
	global_load_lds_dwordx4 v[0:1], off
	v_lshl_add_u64 v[0:1], v[4:5], 0, s[8:9]
	s_mov_b32 m0, s45
	v_readfirstlane_b32 s45, v160
	v_add_u32_e32 v161, s6, v17
	global_load_lds_dwordx4 v[0:1], off
	v_lshl_add_u64 v[0:1], v[6:7], 0, s[8:9]
	s_mov_b32 m0, s45
	v_readfirstlane_b32 s45, v161
	v_add_u32_e32 v162, 0x2000, v161
	global_load_lds_dwordx4 v[0:1], off
	v_lshl_add_u64 v[0:1], v[10:11], 0, s[8:9]
	s_mov_b32 m0, s45
	v_readfirstlane_b32 s45, v162
	global_load_lds_dwordx4 v[0:1], off
	v_lshl_add_u64 v[0:1], v[8:9], 0, s[8:9]
	s_mov_b32 m0, s45
	v_and_b32_e32 v143, 15, v140
	global_load_lds_dwordx4 v[0:1], off
	v_bfe_u32 v142, v140, 4, 2
	v_lshlrev_b32_e32 v3, 2, v140
	v_lshlrev_b32_e32 v0, 4, v142
	v_lshlrev_b32_e32 v1, 6, v143
	v_and_b32_e32 v3, 32, v3
	v_bitop3_b32 v1, v0, v3, v1 bitop3:0x36
	v_readlane_b32 s4, v250, 17
	v_add_u32_e32 v4, s43, v1
	v_add_u32_e32 v6, s5, v1
	v_add_u32_e32 v5, s4, v1
	v_add_u32_e32 v7, s6, v1
	v_add_u32_e32 v9, 0, v1
	v_lshlrev_b32_e32 v1, 6, v140
	s_movk_i32 s4, 0x3c0
	v_and_or_b32 v0, v1, s4, v0
	v_xad_u32 v3, v0, v3, 0
	v_add3_u32 v0, v22, v18, v20
	v_lshl_or_b32 v0, v0, 11, v15
	v_add_u32_sdwa v0, v0, sext(v14) dst_sel:DWORD dst_unused:UNUSED_PAD src0_sel:DWORD src1_sel:WORD_0
	v_mov_b32_e32 v1, v169
	v_lshl_add_u64 v[132:133], v[0:1], 1, s[46:47]
	v_add3_u32 v0, v23, v19, v21
	v_lshl_or_b32 v0, v0, 11, v24
	v_add_u32_sdwa v0, v0, sext(v16) dst_sel:DWORD dst_unused:UNUSED_PAD src0_sel:DWORD src1_sel:WORD_0
	v_lshl_add_u64 v[134:135], v[0:1], 1, s[46:47]
	s_sub_i32 s45, s59, s81
	s_lshl_b32 s46, s80, 8
	s_sub_i32 s45, s45, s46
	s_sext_i32_i16 s45, s45
	v_lshlrev_b32_e32 v0, 14, v12
	s_lshl_b32 s43, s80, 11
	s_lshl_b32 s45, s45, 8
	v_and_b32_e32 v0, 0xffff8000, v0
	s_add_i32 s46, s43, s45
	v_lshl_add_u32 v0, v13, 11, v0
	s_ashr_i32 s47, s46, 31
	v_or_b32_e32 v0, v0, v15
	v_bfe_u32 v141, v140, 6, 2
	s_waitcnt vmcnt(6)
	v_lshlrev_b32_e32 v8, 13, v25
	s_lshl_b64 s[46:47], s[46:47], 12
	v_add_u32_sdwa v0, v0, sext(v14) dst_sel:DWORD dst_unused:UNUSED_PAD src0_sel:DWORD src1_sel:WORD_0
	v_lshlrev_b32_e32 v2, 12, v141
	v_or_b32_e32 v10, 0x800, v8
	v_or_b32_e32 v11, 0x1000, v8
	v_or_b32_e32 v17, 0x1800, v8
	v_lshl_add_u64 v[136:137], v[0:1], 1, s[46:47]
	v_mov_b32_e32 v0, 0
	v_lshlrev_b32_e32 v144, 6, v25
	v_lshl_add_u64 v[138:139], v[168:169], 1, s[46:47]
	s_mov_b32 s43, -2
	v_add_u32_e32 v164, v4, v2
	v_add_u32_e32 v149, v9, v8
	v_add_u32_e32 v148, v3, v10
	v_add_u32_e32 v147, v3, v11
	v_add_u32_e32 v146, v3, v17
	v_add_u32_e32 v163, v5, v2
	v_add_u32_e32 v156, v6, v2
	v_add_u32_e32 v152, v7, v2
	s_mov_b64 s[46:47], s[40:41]
	v_mov_b32_e32 v1, v0
	v_mov_b32_e32 v2, v0
	v_mov_b32_e32 v3, v0
	v_mov_b32_e32 v4, v0
	v_mov_b32_e32 v5, v0
	v_mov_b32_e32 v6, v0
	v_mov_b32_e32 v7, v0
	v_mov_b32_e32 v8, v0
	v_mov_b32_e32 v9, v0
	v_mov_b32_e32 v10, v0
	v_mov_b32_e32 v11, v0
	v_mov_b32_e32 v12, v0
	v_mov_b32_e32 v13, v0
	v_mov_b32_e32 v14, v0
	v_mov_b32_e32 v15, v0
	v_mov_b32_e32 v16, v0
	v_mov_b32_e32 v17, v0
	v_mov_b32_e32 v18, v0
	v_mov_b32_e32 v19, v0
	v_mov_b32_e32 v20, v0
	v_mov_b32_e32 v21, v0
	v_mov_b32_e32 v22, v0
	v_mov_b32_e32 v23, v0
	v_mov_b32_e32 v24, v0
	v_mov_b32_e32 v25, v0
	v_mov_b32_e32 v26, v0
	v_mov_b32_e32 v27, v0
	v_mov_b32_e32 v28, v0
	v_mov_b32_e32 v29, v0
	v_mov_b32_e32 v30, v0
	v_mov_b32_e32 v31, v0
	v_mov_b32_e32 v32, v0
	v_mov_b32_e32 v33, v0
	v_mov_b32_e32 v34, v0
	v_mov_b32_e32 v35, v0
	v_mov_b32_e32 v36, v0
	v_mov_b32_e32 v37, v0
	v_mov_b32_e32 v38, v0
	v_mov_b32_e32 v39, v0
	v_mov_b32_e32 v40, v0
	v_mov_b32_e32 v41, v0
	v_mov_b32_e32 v42, v0
	v_mov_b32_e32 v43, v0
	v_mov_b32_e32 v44, v0
	v_mov_b32_e32 v45, v0
	v_mov_b32_e32 v46, v0
	v_mov_b32_e32 v47, v0
	v_mov_b32_e32 v48, v0
	v_mov_b32_e32 v49, v0
	v_mov_b32_e32 v50, v0
	v_mov_b32_e32 v51, v0
	v_mov_b32_e32 v52, v0
	v_mov_b32_e32 v53, v0
	v_mov_b32_e32 v54, v0
	v_mov_b32_e32 v55, v0
	v_mov_b32_e32 v56, v0
	v_mov_b32_e32 v57, v0
	v_mov_b32_e32 v58, v0
	v_mov_b32_e32 v59, v0
	v_mov_b32_e32 v60, v0
	v_mov_b32_e32 v61, v0
	v_mov_b32_e32 v62, v0
	v_mov_b32_e32 v63, v0
	v_mov_b32_e32 v64, v0
	v_mov_b32_e32 v65, v0
	v_mov_b32_e32 v66, v0
	v_mov_b32_e32 v67, v0
	v_mov_b32_e32 v68, v0
	v_mov_b32_e32 v69, v0
	v_mov_b32_e32 v70, v0
	v_mov_b32_e32 v71, v0
	v_mov_b32_e32 v72, v0
	v_mov_b32_e32 v73, v0
	v_mov_b32_e32 v74, v0
	v_mov_b32_e32 v75, v0
	v_mov_b32_e32 v76, v0
	v_mov_b32_e32 v77, v0
	v_mov_b32_e32 v78, v0
	v_mov_b32_e32 v79, v0
	v_mov_b32_e32 v80, v0
	v_mov_b32_e32 v81, v0
	v_mov_b32_e32 v82, v0
	v_mov_b32_e32 v83, v0
	v_mov_b32_e32 v84, v0
	v_mov_b32_e32 v85, v0
	v_mov_b32_e32 v86, v0
	v_mov_b32_e32 v87, v0
	v_mov_b32_e32 v88, v0
	v_mov_b32_e32 v89, v0
	v_mov_b32_e32 v90, v0
	v_mov_b32_e32 v91, v0
	v_mov_b32_e32 v92, v0
	v_mov_b32_e32 v93, v0
	v_mov_b32_e32 v94, v0
	v_mov_b32_e32 v95, v0
	v_mov_b32_e32 v96, v0
	v_mov_b32_e32 v97, v0
	v_mov_b32_e32 v98, v0
	v_mov_b32_e32 v99, v0
	v_mov_b32_e32 v100, v0
	v_mov_b32_e32 v101, v0
	v_mov_b32_e32 v102, v0
	v_mov_b32_e32 v103, v0
	v_mov_b32_e32 v104, v0
	v_mov_b32_e32 v105, v0
	v_mov_b32_e32 v106, v0
	v_mov_b32_e32 v107, v0
	v_mov_b32_e32 v108, v0
	v_mov_b32_e32 v109, v0
	v_mov_b32_e32 v110, v0
	v_mov_b32_e32 v111, v0
	v_mov_b32_e32 v112, v0
	v_mov_b32_e32 v113, v0
	v_mov_b32_e32 v114, v0
	v_mov_b32_e32 v115, v0
	v_mov_b32_e32 v116, v0
	v_mov_b32_e32 v117, v0
	v_mov_b32_e32 v118, v0
	v_mov_b32_e32 v119, v0
	v_mov_b32_e32 v120, v0
	v_mov_b32_e32 v121, v0
	v_mov_b32_e32 v122, v0
	v_mov_b32_e32 v123, v0
	v_mov_b32_e32 v124, v0
	v_mov_b32_e32 v125, v0
	v_mov_b32_e32 v126, v0
	v_mov_b32_e32 v127, v0
	s_barrier
	.p2align 6

.LBB0_1197:
	s_or_b64 exec, exec, s[46:47]
	v_readlane_b32 s4, v250, 18
	s_mov_b64 s[6:7], 0x80
	v_lshl_add_u64 v[0:1], v[0:1], 0, s[6:7]
	v_add_u32_e32 v155, s4, v17
	v_add_u32_e32 v156, 0x2000, v155
	v_readfirstlane_b32 s37, v155
	s_mov_b32 m0, s37
	v_readfirstlane_b32 s37, v156
	v_add_u32_e32 v157, 0x8000, v148
	s_waitcnt vmcnt(4)
	s_barrier
	global_load_lds_dwordx4 v[0:1], off
	v_lshl_add_u64 v[0:1], v[2:3], 0, s[6:7]
	s_mov_b32 m0, s37
	v_readfirstlane_b32 s37, v157
	v_add_u32_e32 v158, 0xa000, v148
	v_readlane_b32 s5, v250, 19
	global_load_lds_dwordx4 v[0:1], off
	v_lshl_add_u64 v[0:1], v[4:5], 0, s[6:7]
	s_mov_b32 m0, s37
	v_readfirstlane_b32 s37, v158
	v_add_u32_e32 v159, s5, v17
	global_load_lds_dwordx4 v[0:1], off
	v_lshl_add_u64 v[0:1], v[6:7], 0, s[6:7]
	s_mov_b32 m0, s37
	v_readfirstlane_b32 s37, v159
	v_add_u32_e32 v160, 0x2000, v159
	global_load_lds_dwordx4 v[0:1], off
	v_lshl_add_u64 v[0:1], v[10:11], 0, s[6:7]
	s_mov_b32 m0, s37
	v_readfirstlane_b32 s37, v160
	global_load_lds_dwordx4 v[0:1], off
	v_lshl_add_u64 v[0:1], v[8:9], 0, s[6:7]
	s_mov_b32 m0, s37
	v_and_b32_e32 v141, 15, v138
	global_load_lds_dwordx4 v[0:1], off
	v_bfe_u32 v140, v138, 4, 2
	v_lshlrev_b32_e32 v3, 2, v138
	v_lshlrev_b32_e32 v0, 4, v140
	v_lshlrev_b32_e32 v1, 6, v141
	v_and_b32_e32 v3, 32, v3
	v_bitop3_b32 v1, v0, v3, v1 bitop3:0x36
	v_add_u32_e32 v4, s1, v1
	v_readlane_b32 s1, v250, 17
	v_add_u32_e32 v6, s4, v1
	v_add_u32_e32 v7, s5, v1
	v_add_u32_e32 v5, s1, v1
	v_add_u32_e32 v9, 0, v1
	v_lshlrev_b32_e32 v1, 6, v138
	s_movk_i32 s1, 0x3c0
	v_and_or_b32 v0, v1, s1, v0
	v_xad_u32 v3, v0, v3, 0
	v_add3_u32 v0, v22, v18, v20
	v_lshl_or_b32 v0, v0, 13, v15
	v_add_u32_sdwa v0, v0, sext(v14) dst_sel:DWORD dst_unused:UNUSED_PAD src0_sel:DWORD src1_sel:WORD_0
	v_mov_b32_e32 v1, v169
	v_lshl_add_u64 v[130:131], v[0:1], 1, s[44:45]
	v_add3_u32 v0, v23, v19, v21
	v_lshl_or_b32 v0, v0, 13, v24
	v_add_u32_sdwa v0, v0, sext(v16) dst_sel:DWORD dst_unused:UNUSED_PAD src0_sel:DWORD src1_sel:WORD_0
	v_lshl_add_u64 v[132:133], v[0:1], 1, s[44:45]
	s_sub_i32 s37, s58, s80
	s_lshl_b32 s44, s59, 6
	s_sub_i32 s37, s37, s44
	s_sext_i32_i8 s37, s37
	v_lshlrev_b32_e32 v0, 16, v12
	s_lshl_b32 s1, s59, 11
	s_lshl_b32 s37, s37, 8
	v_and_b32_e32 v0, 0xfffe0000, v0
	s_add_i32 s44, s1, s37
	v_lshl_add_u32 v0, v13, 13, v0
	s_ashr_i32 s45, s44, 31
	v_or_b32_e32 v0, v0, v15
	v_bfe_u32 v139, v138, 6, 2
	s_waitcnt vmcnt(6)
	v_lshlrev_b32_e32 v8, 13, v25
	s_lshl_b64 s[44:45], s[44:45], 14
	v_add_u32_sdwa v0, v0, sext(v14) dst_sel:DWORD dst_unused:UNUSED_PAD src0_sel:DWORD src1_sel:WORD_0
	v_lshlrev_b32_e32 v2, 12, v139
	v_or_b32_e32 v10, 0x800, v8
	v_or_b32_e32 v11, 0x1000, v8
	v_or_b32_e32 v17, 0x1800, v8
	v_lshl_add_u64 v[134:135], v[0:1], 1, s[44:45]
	v_mov_b32_e32 v0, 0
	v_lshlrev_b32_e32 v142, 6, v25
	v_lshl_add_u64 v[136:137], v[128:129], 1, s[44:45]
	s_mov_b32 s1, -2
	v_add_u32_e32 v162, v4, v2
	v_add_u32_e32 v147, v9, v8
	v_add_u32_e32 v146, v3, v10
	v_add_u32_e32 v145, v3, v11
	v_add_u32_e32 v144, v3, v17
	v_add_u32_e32 v161, v5, v2
	v_add_u32_e32 v153, v6, v2
	v_add_u32_e32 v150, v7, v2
	s_mov_b64 s[44:45], s[40:41]
	v_mov_b32_e32 v1, v0
	v_mov_b32_e32 v2, v0
	v_mov_b32_e32 v3, v0
	v_mov_b32_e32 v4, v0
	v_mov_b32_e32 v5, v0
	v_mov_b32_e32 v6, v0
	v_mov_b32_e32 v7, v0
	v_mov_b32_e32 v8, v0
	v_mov_b32_e32 v9, v0
	v_mov_b32_e32 v10, v0
	v_mov_b32_e32 v11, v0
	v_mov_b32_e32 v12, v0
	v_mov_b32_e32 v13, v0
	v_mov_b32_e32 v14, v0
	v_mov_b32_e32 v15, v0
	v_mov_b32_e32 v16, v0
	v_mov_b32_e32 v17, v0
	v_mov_b32_e32 v18, v0
	v_mov_b32_e32 v19, v0
	v_mov_b32_e32 v20, v0
	v_mov_b32_e32 v21, v0
	v_mov_b32_e32 v22, v0
	v_mov_b32_e32 v23, v0
	v_mov_b32_e32 v24, v0
	v_mov_b32_e32 v25, v0
	v_mov_b32_e32 v26, v0
	v_mov_b32_e32 v27, v0
	v_mov_b32_e32 v28, v0
	v_mov_b32_e32 v29, v0
	v_mov_b32_e32 v30, v0
	v_mov_b32_e32 v31, v0
	v_mov_b32_e32 v32, v0
	v_mov_b32_e32 v33, v0
	v_mov_b32_e32 v34, v0
	v_mov_b32_e32 v35, v0
	v_mov_b32_e32 v36, v0
	v_mov_b32_e32 v37, v0
	v_mov_b32_e32 v38, v0
	v_mov_b32_e32 v39, v0
	v_mov_b32_e32 v40, v0
	v_mov_b32_e32 v41, v0
	v_mov_b32_e32 v42, v0
	v_mov_b32_e32 v43, v0
	v_mov_b32_e32 v44, v0
	v_mov_b32_e32 v45, v0
	v_mov_b32_e32 v46, v0
	v_mov_b32_e32 v47, v0
	v_mov_b32_e32 v48, v0
	v_mov_b32_e32 v49, v0
	v_mov_b32_e32 v50, v0
	v_mov_b32_e32 v51, v0
	v_mov_b32_e32 v52, v0
	v_mov_b32_e32 v53, v0
	v_mov_b32_e32 v54, v0
	v_mov_b32_e32 v55, v0
	v_mov_b32_e32 v56, v0
	v_mov_b32_e32 v57, v0
	v_mov_b32_e32 v58, v0
	v_mov_b32_e32 v59, v0
	v_mov_b32_e32 v60, v0
	v_mov_b32_e32 v61, v0
	v_mov_b32_e32 v62, v0
	v_mov_b32_e32 v63, v0
	v_mov_b32_e32 v64, v0
	v_mov_b32_e32 v65, v0
	v_mov_b32_e32 v66, v0
	v_mov_b32_e32 v67, v0
	v_mov_b32_e32 v68, v0
	v_mov_b32_e32 v69, v0
	v_mov_b32_e32 v70, v0
	v_mov_b32_e32 v71, v0
	v_mov_b32_e32 v72, v0
	v_mov_b32_e32 v73, v0
	v_mov_b32_e32 v74, v0
	v_mov_b32_e32 v75, v0
	v_mov_b32_e32 v76, v0
	v_mov_b32_e32 v77, v0
	v_mov_b32_e32 v78, v0
	v_mov_b32_e32 v79, v0
	v_mov_b32_e32 v80, v0
	v_mov_b32_e32 v81, v0
	v_mov_b32_e32 v82, v0
	v_mov_b32_e32 v83, v0
	v_mov_b32_e32 v84, v0
	v_mov_b32_e32 v85, v0
	v_mov_b32_e32 v86, v0
	v_mov_b32_e32 v87, v0
	v_mov_b32_e32 v88, v0
	v_mov_b32_e32 v89, v0
	v_mov_b32_e32 v90, v0
	v_mov_b32_e32 v91, v0
	v_mov_b32_e32 v92, v0
	v_mov_b32_e32 v93, v0
	v_mov_b32_e32 v94, v0
	v_mov_b32_e32 v95, v0
	v_mov_b32_e32 v96, v0
	v_mov_b32_e32 v97, v0
	v_mov_b32_e32 v98, v0
	v_mov_b32_e32 v99, v0
	v_mov_b32_e32 v100, v0
	v_mov_b32_e32 v101, v0
	v_mov_b32_e32 v102, v0
	v_mov_b32_e32 v103, v0
	v_mov_b32_e32 v104, v0
	v_mov_b32_e32 v105, v0
	v_mov_b32_e32 v106, v0
	v_mov_b32_e32 v107, v0
	v_mov_b32_e32 v108, v0
	v_mov_b32_e32 v109, v0
	v_mov_b32_e32 v110, v0
	v_mov_b32_e32 v111, v0
	v_mov_b32_e32 v112, v0
	v_mov_b32_e32 v113, v0
	v_mov_b32_e32 v114, v0
	v_mov_b32_e32 v115, v0
	v_mov_b32_e32 v116, v0
	v_mov_b32_e32 v117, v0
	v_mov_b32_e32 v118, v0
	v_mov_b32_e32 v119, v0
	v_mov_b32_e32 v120, v0
	v_mov_b32_e32 v121, v0
	v_mov_b32_e32 v122, v0
	v_mov_b32_e32 v123, v0
	v_mov_b32_e32 v124, v0
	v_mov_b32_e32 v125, v0
	v_mov_b32_e32 v126, v0
	v_mov_b32_e32 v127, v0
	s_mov_b64 s[4:5], 0x26da8100
	s_barrier
	.p2align 6
